# S5 scan loop hand-scheduled: x prefetched from LDS with counted lgkmcnt, MFMAs batched
# speedup vs baseline: 1.0096x; 1.0096x over previous
.LBB0_844:
	s_or_b64 exec, exec, s[12:13]
	v_mfma_f32_16x16x32_bf16 v[132:135], v[4:7], v[68:71], 0
	v_mfma_f32_16x16x32_bf16 v[136:139], v[8:11], v[68:71], 0
	v_mfma_f32_16x16x32_bf16 v[140:143], v[12:15], v[68:71], 0
	v_mfma_f32_16x16x32_bf16 v[144:147], v[16:19], v[68:71], 0
	v_mfma_f32_16x16x32_bf16 v[148:151], v[20:23], v[68:71], 0
	v_mfma_f32_16x16x32_bf16 v[152:155], v[24:27], v[68:71], 0
	v_mfma_f32_16x16x32_bf16 v[156:159], v[28:31], v[68:71], 0
	v_mfma_f32_16x16x32_bf16 v[160:163], v[32:35], v[68:71], 0
	v_add_u32_e32 v196, v89, v93
	ds_write_b128 v196, v[132:135]
	ds_write_b128 v196, v[136:139] offset:64
	ds_write_b128 v196, v[140:143] offset:128
	ds_write_b128 v196, v[144:147] offset:192
	ds_write_b128 v196, v[148:151] offset:256
	ds_write_b128 v196, v[152:155] offset:320
	ds_write_b128 v196, v[156:159] offset:384
	ds_write_b128 v196, v[160:163] offset:448
	s_waitcnt lgkmcnt(0)
	s_and_b64 s[14:15], s[0:1], exec
	s_cbranch_scc0 .Ls5c_bwd
	ds_read_b64 v[164:165], v95
	ds_read_b64 v[166:167], v95 offset:528
	ds_read_b64 v[168:169], v95 offset:1056
	ds_read_b64 v[170:171], v95 offset:1584
	ds_read_b64 v[172:173], v95 offset:2112
	ds_read_b64 v[174:175], v95 offset:2640
	ds_read_b64 v[176:177], v95 offset:3168
	ds_read_b64 v[178:179], v95 offset:3696
	s_waitcnt lgkmcnt(7)
	v_fma_f32 v164, -v72, v121, v164
	v_fma_f32 v165, v72, v120, v165
	v_fma_f32 v164, v74, v120, v164
	v_fma_f32 v165, v74, v121, v165
	v_cvt_pk_bf16_f32 v197, v164, v165
	ds_write_b32 v97, v197 offset:8448
	ds_read_b64 v[180:181], v95 offset:4224
	s_waitcnt lgkmcnt(8)
	v_fma_f32 v166, -v72, v165, v166
	v_fma_f32 v167, v72, v164, v167
	v_fma_f32 v166, v74, v164, v166
	v_fma_f32 v167, v74, v165, v167
	v_cvt_pk_bf16_f32 v198, v166, v167
	ds_write_b32 v97, v198 offset:8720
	ds_read_b64 v[182:183], v95 offset:4752
	s_waitcnt lgkmcnt(9)
	v_fma_f32 v168, -v72, v167, v168
	v_fma_f32 v169, v72, v166, v169
	v_fma_f32 v168, v74, v166, v168
	v_fma_f32 v169, v74, v167, v169
	v_cvt_pk_bf16_f32 v197, v168, v169
	ds_write_b32 v97, v197 offset:8992
	ds_read_b64 v[184:185], v95 offset:5280
	s_waitcnt lgkmcnt(10)
	v_fma_f32 v170, -v72, v169, v170
	v_fma_f32 v171, v72, v168, v171
	v_fma_f32 v170, v74, v168, v170
	v_fma_f32 v171, v74, v169, v171
	v_cvt_pk_bf16_f32 v198, v170, v171
	ds_write_b32 v97, v198 offset:9264
	ds_read_b64 v[186:187], v95 offset:5808
	s_waitcnt lgkmcnt(11)
	v_fma_f32 v172, -v72, v171, v172
	v_fma_f32 v173, v72, v170, v173
	v_fma_f32 v172, v74, v170, v172
	v_fma_f32 v173, v74, v171, v173
	v_cvt_pk_bf16_f32 v197, v172, v173
	ds_write_b32 v97, v197 offset:9536
	ds_read_b64 v[188:189], v95 offset:6336
	s_waitcnt lgkmcnt(12)
	v_fma_f32 v174, -v72, v173, v174
	v_fma_f32 v175, v72, v172, v175
	v_fma_f32 v174, v74, v172, v174
	v_fma_f32 v175, v74, v173, v175
	v_cvt_pk_bf16_f32 v198, v174, v175
	ds_write_b32 v97, v198 offset:9808
	ds_read_b64 v[190:191], v95 offset:6864
	s_waitcnt lgkmcnt(13)
	v_fma_f32 v176, -v72, v175, v176
	v_fma_f32 v177, v72, v174, v177
	v_fma_f32 v176, v74, v174, v176
	v_fma_f32 v177, v74, v175, v177
	v_cvt_pk_bf16_f32 v197, v176, v177
	ds_write_b32 v97, v197 offset:10080
	ds_read_b64 v[192:193], v95 offset:7392
	s_waitcnt lgkmcnt(14)
	v_fma_f32 v178, -v72, v177, v178
	v_fma_f32 v179, v72, v176, v179
	v_fma_f32 v178, v74, v176, v178
	v_fma_f32 v179, v74, v177, v179
	v_cvt_pk_bf16_f32 v198, v178, v179
	ds_write_b32 v97, v198 offset:10352
	ds_read_b64 v[194:195], v95 offset:7920
	s_waitcnt lgkmcnt(14)
	v_fma_f32 v180, -v72, v179, v180
	v_fma_f32 v181, v72, v178, v181
	v_fma_f32 v180, v74, v178, v180
	v_fma_f32 v181, v74, v179, v181
	v_cvt_pk_bf16_f32 v197, v180, v181
	ds_write_b32 v97, v197 offset:10624
	s_waitcnt lgkmcnt(13)
	v_fma_f32 v182, -v72, v181, v182
	v_fma_f32 v183, v72, v180, v183
	v_fma_f32 v182, v74, v180, v182
	v_fma_f32 v183, v74, v181, v183
	v_cvt_pk_bf16_f32 v198, v182, v183
	ds_write_b32 v97, v198 offset:10896
	s_waitcnt lgkmcnt(12)
	v_fma_f32 v184, -v72, v183, v184
	v_fma_f32 v185, v72, v182, v185
	v_fma_f32 v184, v74, v182, v184
	v_fma_f32 v185, v74, v183, v185
	v_cvt_pk_bf16_f32 v197, v184, v185
	ds_write_b32 v97, v197 offset:11168
	s_waitcnt lgkmcnt(11)
	v_fma_f32 v186, -v72, v185, v186
	v_fma_f32 v187, v72, v184, v187
	v_fma_f32 v186, v74, v184, v186
	v_fma_f32 v187, v74, v185, v187
	v_cvt_pk_bf16_f32 v198, v186, v187
	ds_write_b32 v97, v198 offset:11440
	s_waitcnt lgkmcnt(10)
	v_fma_f32 v188, -v72, v187, v188
	v_fma_f32 v189, v72, v186, v189
	v_fma_f32 v188, v74, v186, v188
	v_fma_f32 v189, v74, v187, v189
	v_cvt_pk_bf16_f32 v197, v188, v189
	ds_write_b32 v97, v197 offset:11712
	s_waitcnt lgkmcnt(9)
	v_fma_f32 v190, -v72, v189, v190
	v_fma_f32 v191, v72, v188, v191
	v_fma_f32 v190, v74, v188, v190
	v_fma_f32 v191, v74, v189, v191
	v_cvt_pk_bf16_f32 v198, v190, v191
	ds_write_b32 v97, v198 offset:11984
	s_waitcnt lgkmcnt(8)
	v_fma_f32 v192, -v72, v191, v192
	v_fma_f32 v193, v72, v190, v193
	v_fma_f32 v192, v74, v190, v192
	v_fma_f32 v193, v74, v191, v193
	v_cvt_pk_bf16_f32 v197, v192, v193
	ds_write_b32 v97, v197 offset:12256
	s_waitcnt lgkmcnt(7)
	v_fma_f32 v194, -v72, v193, v194
	v_fma_f32 v195, v72, v192, v195
	v_fma_f32 v194, v74, v192, v194
	v_fma_f32 v195, v74, v193, v195
	v_cvt_pk_bf16_f32 v198, v194, v195
	ds_write_b32 v97, v198 offset:12528
	s_branch .Ls5c_join
.Ls5c_bwd:
	ds_read_b64 v[164:165], v95 offset:7920
	ds_read_b64 v[166:167], v95 offset:7392
	ds_read_b64 v[168:169], v95 offset:6864
	ds_read_b64 v[170:171], v95 offset:6336
	ds_read_b64 v[172:173], v95 offset:5808
	ds_read_b64 v[174:175], v95 offset:5280
	ds_read_b64 v[176:177], v95 offset:4752
	ds_read_b64 v[178:179], v95 offset:4224
	s_waitcnt lgkmcnt(7)
	v_fma_f32 v164, -v72, v121, v164
	v_fma_f32 v165, v72, v120, v165
	v_fma_f32 v164, v74, v120, v164
	v_fma_f32 v165, v74, v121, v165
	v_cvt_pk_bf16_f32 v197, v164, v165
	ds_write_b32 v97, v197 offset:12528
	ds_read_b64 v[180:181], v95 offset:3696
	s_waitcnt lgkmcnt(8)
	v_fma_f32 v166, -v72, v165, v166
	v_fma_f32 v167, v72, v164, v167
	v_fma_f32 v166, v74, v164, v166
	v_fma_f32 v167, v74, v165, v167
	v_cvt_pk_bf16_f32 v198, v166, v167
	ds_write_b32 v97, v198 offset:12256
	ds_read_b64 v[182:183], v95 offset:3168
	s_waitcnt lgkmcnt(9)
	v_fma_f32 v168, -v72, v167, v168
	v_fma_f32 v169, v72, v166, v169
	v_fma_f32 v168, v74, v166, v168
	v_fma_f32 v169, v74, v167, v169
	v_cvt_pk_bf16_f32 v197, v168, v169
	ds_write_b32 v97, v197 offset:11984
	ds_read_b64 v[184:185], v95 offset:2640
	s_waitcnt lgkmcnt(10)
	v_fma_f32 v170, -v72, v169, v170
	v_fma_f32 v171, v72, v168, v171
	v_fma_f32 v170, v74, v168, v170
	v_fma_f32 v171, v74, v169, v171
	v_cvt_pk_bf16_f32 v198, v170, v171
	ds_write_b32 v97, v198 offset:11712
	ds_read_b64 v[186:187], v95 offset:2112
	s_waitcnt lgkmcnt(11)
	v_fma_f32 v172, -v72, v171, v172
	v_fma_f32 v173, v72, v170, v173
	v_fma_f32 v172, v74, v170, v172
	v_fma_f32 v173, v74, v171, v173
	v_cvt_pk_bf16_f32 v197, v172, v173
	ds_write_b32 v97, v197 offset:11440
	ds_read_b64 v[188:189], v95 offset:1584
	s_waitcnt lgkmcnt(12)
	v_fma_f32 v174, -v72, v173, v174
	v_fma_f32 v175, v72, v172, v175
	v_fma_f32 v174, v74, v172, v174
	v_fma_f32 v175, v74, v173, v175
	v_cvt_pk_bf16_f32 v198, v174, v175
	ds_write_b32 v97, v198 offset:11168
	ds_read_b64 v[190:191], v95 offset:1056
	s_waitcnt lgkmcnt(13)
	v_fma_f32 v176, -v72, v175, v176
	v_fma_f32 v177, v72, v174, v177
	v_fma_f32 v176, v74, v174, v176
	v_fma_f32 v177, v74, v175, v177
	v_cvt_pk_bf16_f32 v197, v176, v177
	ds_write_b32 v97, v197 offset:10896
	ds_read_b64 v[192:193], v95 offset:528
	s_waitcnt lgkmcnt(14)
	v_fma_f32 v178, -v72, v177, v178
	v_fma_f32 v179, v72, v176, v179
	v_fma_f32 v178, v74, v176, v178
	v_fma_f32 v179, v74, v177, v179
	v_cvt_pk_bf16_f32 v198, v178, v179
	ds_write_b32 v97, v198 offset:10624
	ds_read_b64 v[194:195], v95
	s_waitcnt lgkmcnt(14)
	v_fma_f32 v180, -v72, v179, v180
	v_fma_f32 v181, v72, v178, v181
	v_fma_f32 v180, v74, v178, v180
	v_fma_f32 v181, v74, v179, v181
	v_cvt_pk_bf16_f32 v197, v180, v181
	ds_write_b32 v97, v197 offset:10352
	s_waitcnt lgkmcnt(13)
	v_fma_f32 v182, -v72, v181, v182
	v_fma_f32 v183, v72, v180, v183
	v_fma_f32 v182, v74, v180, v182
	v_fma_f32 v183, v74, v181, v183
	v_cvt_pk_bf16_f32 v198, v182, v183
	ds_write_b32 v97, v198 offset:10080
	s_waitcnt lgkmcnt(12)
	v_fma_f32 v184, -v72, v183, v184
	v_fma_f32 v185, v72, v182, v185
	v_fma_f32 v184, v74, v182, v184
	v_fma_f32 v185, v74, v183, v185
	v_cvt_pk_bf16_f32 v197, v184, v185
	ds_write_b32 v97, v197 offset:9808
	s_waitcnt lgkmcnt(11)
	v_fma_f32 v186, -v72, v185, v186
	v_fma_f32 v187, v72, v184, v187
	v_fma_f32 v186, v74, v184, v186
	v_fma_f32 v187, v74, v185, v187
	v_cvt_pk_bf16_f32 v198, v186, v187
	ds_write_b32 v97, v198 offset:9536
	s_waitcnt lgkmcnt(10)
	v_fma_f32 v188, -v72, v187, v188
	v_fma_f32 v189, v72, v186, v189
	v_fma_f32 v188, v74, v186, v188
	v_fma_f32 v189, v74, v187, v189
	v_cvt_pk_bf16_f32 v197, v188, v189
	ds_write_b32 v97, v197 offset:9264
	s_waitcnt lgkmcnt(9)
	v_fma_f32 v190, -v72, v189, v190
	v_fma_f32 v191, v72, v188, v191
	v_fma_f32 v190, v74, v188, v190
	v_fma_f32 v191, v74, v189, v191
	v_cvt_pk_bf16_f32 v198, v190, v191
	ds_write_b32 v97, v198 offset:8992
	s_waitcnt lgkmcnt(8)
	v_fma_f32 v192, -v72, v191, v192
	v_fma_f32 v193, v72, v190, v193
	v_fma_f32 v192, v74, v190, v192
	v_fma_f32 v193, v74, v191, v193
	v_cvt_pk_bf16_f32 v197, v192, v193
	ds_write_b32 v97, v197 offset:8720
	s_waitcnt lgkmcnt(7)
	v_fma_f32 v194, -v72, v193, v194
	v_fma_f32 v195, v72, v192, v195
	v_fma_f32 v194, v74, v192, v194
	v_fma_f32 v195, v74, v193, v195
	v_cvt_pk_bf16_f32 v198, v194, v195
	ds_write_b32 v97, v198 offset:8448
.Ls5c_join:
	v_mov_b32_e32 v120, v194
	v_mov_b32_e32 v121, v195
	s_waitcnt lgkmcnt(0)
	v_add_u32_e32 v196, v99, v93
	ds_read_b128 v[132:135], v196 offset:8448
	ds_read_b128 v[136:139], v196 offset:8512
	ds_read_b128 v[140:143], v196 offset:8576
	ds_read_b128 v[144:147], v196 offset:8640
	s_not_b32 s14, s3
	s_add_i32 s18, s2, s14
	s_and_b64 s[14:15], s[0:1], exec
	s_cselect_b32 s14, s3, s18
	s_add_i32 s3, s3, 1
	s_waitcnt lgkmcnt(3)
	v_mfma_f32_16x16x32_bf16 v[68:71], v[48:51], v[132:135], 0
	s_waitcnt lgkmcnt(2)
	v_mfma_f32_16x16x32_bf16 v[68:71], v[52:55], v[136:139], v[68:71]
	s_waitcnt lgkmcnt(1)
	v_mfma_f32_16x16x32_bf16 v[68:71], v[56:59], v[140:143], v[68:71]
	s_waitcnt lgkmcnt(0)
	v_mfma_f32_16x16x32_bf16 v[68:71], v[60:63], v[144:147], v[68:71]
	v_lshl_add_u32 v200, s14, 4, v103
	v_ashrrev_i32_e32 v201, 31, v200
	v_lshlrev_b64 v[200:201], 12, v[200:201]
	v_lshl_add_u64 v[200:201], v[78:79], 0, v[200:201]
	s_nop 3
	v_cvt_pk_bf16_f32 v68, v68, v69
	v_cvt_pk_bf16_f32 v69, v70, v71
	global_store_dwordx2 v[200:201], v[68:69], off
	s_cmp_eq_u32 s3, s2
	s_cbranch_scc1 .LBB0_848
	v_mov_b32_e32 v68, v36
	v_mov_b32_e32 v69, v37
	v_mov_b32_e32 v70, v38
	v_mov_b32_e32 v71, v39
	v_mov_b32_e32 v36, v40
	v_mov_b32_e32 v37, v41
	v_mov_b32_e32 v38, v42
	v_mov_b32_e32 v39, v43
	v_mov_b32_e32 v40, v44
	v_mov_b32_e32 v41, v45
	v_mov_b32_e32 v42, v46
	v_mov_b32_e32 v43, v47
	s_waitcnt vmcnt(1)
	v_mov_b32_e32 v44, v64
	v_mov_b32_e32 v45, v65
	v_mov_b32_e32 v46, v66
	v_mov_b32_e32 v47, v67
	s_branch .LBB0_841

.LBB0_912:
	s_or_b64 exec, exec, s[12:13]
	v_mfma_f32_16x16x32_bf16 v[132:135], v[4:7], v[68:71], 0
	v_mfma_f32_16x16x32_bf16 v[136:139], v[8:11], v[68:71], 0
	v_mfma_f32_16x16x32_bf16 v[140:143], v[12:15], v[68:71], 0
	v_mfma_f32_16x16x32_bf16 v[144:147], v[16:19], v[68:71], 0
	v_mfma_f32_16x16x32_bf16 v[148:151], v[20:23], v[68:71], 0
	v_mfma_f32_16x16x32_bf16 v[152:155], v[24:27], v[68:71], 0
	v_mfma_f32_16x16x32_bf16 v[156:159], v[28:31], v[68:71], 0
	v_mfma_f32_16x16x32_bf16 v[160:163], v[32:35], v[68:71], 0
	v_add_u32_e32 v196, v89, v93
	ds_write_b128 v196, v[132:135]
	ds_write_b128 v196, v[136:139] offset:64
	ds_write_b128 v196, v[140:143] offset:128
	ds_write_b128 v196, v[144:147] offset:192
	ds_write_b128 v196, v[148:151] offset:256
	ds_write_b128 v196, v[152:155] offset:320
	ds_write_b128 v196, v[156:159] offset:384
	ds_write_b128 v196, v[160:163] offset:448
	s_waitcnt lgkmcnt(0)
	s_and_b64 s[12:13], s[54:55], exec
	s_cbranch_scc0 .Ls5l_bwd
	ds_read_b64 v[164:165], v95
	ds_read_b64 v[166:167], v95 offset:528
	ds_read_b64 v[168:169], v95 offset:1056
	ds_read_b64 v[170:171], v95 offset:1584
	ds_read_b64 v[172:173], v95 offset:2112
	ds_read_b64 v[174:175], v95 offset:2640
	ds_read_b64 v[176:177], v95 offset:3168
	ds_read_b64 v[178:179], v95 offset:3696
	s_waitcnt lgkmcnt(7)
	v_fma_f32 v164, -v72, v121, v164
	v_fma_f32 v165, v72, v120, v165
	v_fma_f32 v164, v74, v120, v164
	v_fma_f32 v165, v74, v121, v165
	v_cvt_pk_bf16_f32 v197, v164, v165
	ds_write_b32 v97, v197 offset:8448
	ds_read_b64 v[180:181], v95 offset:4224
	s_waitcnt lgkmcnt(8)
	v_fma_f32 v166, -v72, v165, v166
	v_fma_f32 v167, v72, v164, v167
	v_fma_f32 v166, v74, v164, v166
	v_fma_f32 v167, v74, v165, v167
	v_cvt_pk_bf16_f32 v198, v166, v167
	ds_write_b32 v97, v198 offset:8720
	ds_read_b64 v[182:183], v95 offset:4752
	s_waitcnt lgkmcnt(9)
	v_fma_f32 v168, -v72, v167, v168
	v_fma_f32 v169, v72, v166, v169
	v_fma_f32 v168, v74, v166, v168
	v_fma_f32 v169, v74, v167, v169
	v_cvt_pk_bf16_f32 v197, v168, v169
	ds_write_b32 v97, v197 offset:8992
	ds_read_b64 v[184:185], v95 offset:5280
	s_waitcnt lgkmcnt(10)
	v_fma_f32 v170, -v72, v169, v170
	v_fma_f32 v171, v72, v168, v171
	v_fma_f32 v170, v74, v168, v170
	v_fma_f32 v171, v74, v169, v171
	v_cvt_pk_bf16_f32 v198, v170, v171
	ds_write_b32 v97, v198 offset:9264
	ds_read_b64 v[186:187], v95 offset:5808
	s_waitcnt lgkmcnt(11)
	v_fma_f32 v172, -v72, v171, v172
	v_fma_f32 v173, v72, v170, v173
	v_fma_f32 v172, v74, v170, v172
	v_fma_f32 v173, v74, v171, v173
	v_cvt_pk_bf16_f32 v197, v172, v173
	ds_write_b32 v97, v197 offset:9536
	ds_read_b64 v[188:189], v95 offset:6336
	s_waitcnt lgkmcnt(12)
	v_fma_f32 v174, -v72, v173, v174
	v_fma_f32 v175, v72, v172, v175
	v_fma_f32 v174, v74, v172, v174
	v_fma_f32 v175, v74, v173, v175
	v_cvt_pk_bf16_f32 v198, v174, v175
	ds_write_b32 v97, v198 offset:9808
	ds_read_b64 v[190:191], v95 offset:6864
	s_waitcnt lgkmcnt(13)
	v_fma_f32 v176, -v72, v175, v176
	v_fma_f32 v177, v72, v174, v177
	v_fma_f32 v176, v74, v174, v176
	v_fma_f32 v177, v74, v175, v177
	v_cvt_pk_bf16_f32 v197, v176, v177
	ds_write_b32 v97, v197 offset:10080
	ds_read_b64 v[192:193], v95 offset:7392
	s_waitcnt lgkmcnt(14)
	v_fma_f32 v178, -v72, v177, v178
	v_fma_f32 v179, v72, v176, v179
	v_fma_f32 v178, v74, v176, v178
	v_fma_f32 v179, v74, v177, v179
	v_cvt_pk_bf16_f32 v198, v178, v179
	ds_write_b32 v97, v198 offset:10352
	ds_read_b64 v[194:195], v95 offset:7920
	s_waitcnt lgkmcnt(14)
	v_fma_f32 v180, -v72, v179, v180
	v_fma_f32 v181, v72, v178, v181
	v_fma_f32 v180, v74, v178, v180
	v_fma_f32 v181, v74, v179, v181
	v_cvt_pk_bf16_f32 v197, v180, v181
	ds_write_b32 v97, v197 offset:10624
	s_waitcnt lgkmcnt(13)
	v_fma_f32 v182, -v72, v181, v182
	v_fma_f32 v183, v72, v180, v183
	v_fma_f32 v182, v74, v180, v182
	v_fma_f32 v183, v74, v181, v183
	v_cvt_pk_bf16_f32 v198, v182, v183
	ds_write_b32 v97, v198 offset:10896
	s_waitcnt lgkmcnt(12)
	v_fma_f32 v184, -v72, v183, v184
	v_fma_f32 v185, v72, v182, v185
	v_fma_f32 v184, v74, v182, v184
	v_fma_f32 v185, v74, v183, v185
	v_cvt_pk_bf16_f32 v197, v184, v185
	ds_write_b32 v97, v197 offset:11168
	s_waitcnt lgkmcnt(11)
	v_fma_f32 v186, -v72, v185, v186
	v_fma_f32 v187, v72, v184, v187
	v_fma_f32 v186, v74, v184, v186
	v_fma_f32 v187, v74, v185, v187
	v_cvt_pk_bf16_f32 v198, v186, v187
	ds_write_b32 v97, v198 offset:11440
	s_waitcnt lgkmcnt(10)
	v_fma_f32 v188, -v72, v187, v188
	v_fma_f32 v189, v72, v186, v189
	v_fma_f32 v188, v74, v186, v188
	v_fma_f32 v189, v74, v187, v189
	v_cvt_pk_bf16_f32 v197, v188, v189
	ds_write_b32 v97, v197 offset:11712
	s_waitcnt lgkmcnt(9)
	v_fma_f32 v190, -v72, v189, v190
	v_fma_f32 v191, v72, v188, v191
	v_fma_f32 v190, v74, v188, v190
	v_fma_f32 v191, v74, v189, v191
	v_cvt_pk_bf16_f32 v198, v190, v191
	ds_write_b32 v97, v198 offset:11984
	s_waitcnt lgkmcnt(8)
	v_fma_f32 v192, -v72, v191, v192
	v_fma_f32 v193, v72, v190, v193
	v_fma_f32 v192, v74, v190, v192
	v_fma_f32 v193, v74, v191, v193
	v_cvt_pk_bf16_f32 v197, v192, v193
	ds_write_b32 v97, v197 offset:12256
	s_waitcnt lgkmcnt(7)
	v_fma_f32 v194, -v72, v193, v194
	v_fma_f32 v195, v72, v192, v195
	v_fma_f32 v194, v74, v192, v194
	v_fma_f32 v195, v74, v193, v195
	v_cvt_pk_bf16_f32 v198, v194, v195
	ds_write_b32 v97, v198 offset:12528
	s_branch .Ls5l_join

.Ls5l_join:
	v_mov_b32_e32 v120, v194
	v_mov_b32_e32 v121, v195
	s_waitcnt lgkmcnt(0)
	v_add_u32_e32 v196, v99, v93
	ds_read_b128 v[132:135], v196 offset:8448
	ds_read_b128 v[136:139], v196 offset:8512
	ds_read_b128 v[140:143], v196 offset:8576
	ds_read_b128 v[144:147], v196 offset:8640
	s_not_b32 s12, s4
	s_add_i32 s15, s3, s12
	s_and_b64 s[12:13], s[54:55], exec
	s_cselect_b32 s12, s4, s15
	s_add_i32 s4, s4, 1
	s_waitcnt lgkmcnt(3)
	v_mfma_f32_16x16x32_bf16 v[68:71], v[48:51], v[132:135], 0
	s_waitcnt lgkmcnt(2)
	v_mfma_f32_16x16x32_bf16 v[68:71], v[52:55], v[136:139], v[68:71]
	s_waitcnt lgkmcnt(1)
	v_mfma_f32_16x16x32_bf16 v[68:71], v[56:59], v[140:143], v[68:71]
	s_waitcnt lgkmcnt(0)
	v_mfma_f32_16x16x32_bf16 v[68:71], v[60:63], v[144:147], v[68:71]
	v_lshl_add_u32 v200, s12, 4, v2
	v_ashrrev_i32_e32 v201, 31, v200
	v_lshlrev_b64 v[200:201], 12, v[200:201]
	v_lshl_add_u64 v[200:201], v[78:79], 0, v[200:201]
	s_nop 3
	v_cvt_pk_bf16_f32 v68, v68, v69
	v_cvt_pk_bf16_f32 v69, v70, v71
	global_store_dwordx2 v[200:201], v[68:69], off
	s_cmp_eq_u32 s4, s3
	s_cbranch_scc1 .LBB0_916
	v_mov_b32_e32 v68, v36
	v_mov_b32_e32 v69, v37
	v_mov_b32_e32 v70, v38
	v_mov_b32_e32 v71, v39
	v_mov_b32_e32 v36, v40
	v_mov_b32_e32 v37, v41
	v_mov_b32_e32 v38, v42
	v_mov_b32_e32 v39, v43
	v_mov_b32_e32 v40, v44
	v_mov_b32_e32 v41, v45
	v_mov_b32_e32 v42, v46
	v_mov_b32_e32 v43, v47
	s_waitcnt vmcnt(1)
	v_mov_b32_e32 v44, v64
	v_mov_b32_e32 v45, v65
	v_mov_b32_e32 v46, v66
	v_mov_b32_e32 v47, v67
	s_branch .LBB0_909
